# v35 + non-temporal policy on SCAN_C last-use loads (q, log-decay, v, incoming states)
# speedup vs baseline: 1.0108x; 1.0108x over previous
.LBB0_1331:
	v_or_b32_e32 v10, s63, v1
	v_ashrrev_i32_e32 v11, 31, v10
	v_lshl_add_u64 v[12:13], v[150:151], 0, s[26:27]
	v_lshlrev_b64 v[14:15], 11, v[10:11]
	v_lshl_add_u64 v[16:17], v[12:13], 0, v[14:15]
	global_load_dwordx4 v[34:37], v[16:17], off nt
	global_load_dwordx4 v[2:5], v[148:149], off offset:16 nt
	global_load_dwordx4 v[6:9], v[148:149], off nt
	v_and_b32_e32 v11, 64, v169
	v_xor_b32_e32 v22, 1, v169
	v_add_u32_e32 v26, 64, v11
	v_xor_b32_e32 v23, 2, v169
	v_cmp_lt_i32_e32 vcc, v22, v26
	v_xor_b32_e32 v24, 4, v169
	v_xor_b32_e32 v25, 8, v169
	v_cndmask_b32_e32 v22, v169, v22, vcc
	v_cmp_lt_i32_e32 vcc, v23, v26
	v_lshlrev_b32_e32 v41, 2, v22
	ds_read_b128 v[42:45], v170
	ds_read_b128 v[46:49], v171
	v_cndmask_b32_e32 v23, v169, v23, vcc
	v_cmp_lt_i32_e32 vcc, v24, v26
	v_lshlrev_b32_e32 v40, 2, v23
	s_waitcnt lgkmcnt(1)
	v_lshlrev_b32_e32 v56, 16, v45
	v_cndmask_b32_e32 v24, v169, v24, vcc
	v_cmp_lt_i32_e32 vcc, v25, v26
	v_and_b32_e32 v57, 0xffff0000, v45
	v_and_b32_e32 v45, 0xffff0000, v43
	v_cndmask_b32_e32 v25, v169, v25, vcc
	v_add_co_u32_e32 v22, vcc, 0x10000, v16
	v_and_b32_e32 v67, 0xffff0000, v42
	s_nop 0
	v_addc_co_u32_e32 v23, vcc, 0, v17, vcc
	global_load_dwordx4 v[50:53], v[22:23], off nt
	v_lshlrev_b32_e32 v58, 16, v44
	v_and_b32_e32 v59, 0xffff0000, v44
	v_lshlrev_b32_e32 v44, 16, v43
	v_lshlrev_b32_e32 v66, 16, v42
	v_mov_b32_e32 v68, v67
	v_mov_b32_e32 v69, v45
	v_mov_b32_e32 v42, v66
	v_mov_b32_e32 v43, v44
	v_pk_mul_f32 v[68:69], v[68:69], v[68:69]
	s_waitcnt lgkmcnt(0)
	v_and_b32_e32 v71, 0xffff0000, v48
	v_pk_fma_f32 v[42:43], v[42:43], v[42:43], v[68:69]
	v_and_b32_e32 v69, 0xffff0000, v49
	v_or_b32_e32 v18, 64, v10
	v_or_b32_e32 v20, 0x80, v10
	v_or_b32_e32 v10, 0xc0, v10
	v_lshlrev_b32_e32 v68, 16, v49
	v_lshlrev_b32_e32 v70, 16, v48
	v_mov_b32_e32 v72, v69
	v_mov_b32_e32 v73, v71
	v_ashrrev_i32_e32 v19, 31, v18
	v_ashrrev_i32_e32 v21, 31, v20
	v_ashrrev_i32_e32 v11, 31, v10
	v_mov_b32_e32 v48, v68
	v_mov_b32_e32 v49, v70
	v_pk_mul_f32 v[72:73], v[72:73], v[72:73]
	v_lshlrev_b64 v[18:19], 11, v[18:19]
	v_lshlrev_b64 v[20:21], 11, v[20:21]
	v_lshlrev_b64 v[10:11], 11, v[10:11]
	v_lshl_add_u64 v[14:15], s[22:23], 0, v[14:15]
	v_pk_fma_f32 v[48:49], v[48:49], v[48:49], v[72:73]
	v_and_b32_e32 v73, 0xffff0000, v47
	v_and_b32_e32 v75, 0xffff0000, v46
	v_lshl_add_u64 v[18:19], v[12:13], 0, v[18:19]
	v_lshl_add_u64 v[20:21], v[12:13], 0, v[20:21]
	v_lshl_add_u64 v[10:11], v[12:13], 0, v[10:11]
	v_lshl_add_u64 v[12:13], v[14:15], 0, s[26:27]
	v_add_co_u32_e32 v14, vcc, s46, v16
	v_lshlrev_b32_e32 v72, 16, v47
	v_lshlrev_b32_e32 v74, 16, v46
	v_mov_b32_e32 v76, v75
	v_mov_b32_e32 v77, v73
	v_addc_co_u32_e32 v15, vcc, 0, v17, vcc
	v_mov_b32_e32 v22, v57
	v_mov_b32_e32 v23, v59
	v_mov_b32_e32 v46, v74
	v_mov_b32_e32 v47, v72
	v_pk_mul_f32 v[76:77], v[76:77], v[76:77]
	v_mov_b32_e32 v60, v56
	v_mov_b32_e32 v61, v58
	global_load_dwordx4 v[30:33], v[18:19], off nt
	global_load_dwordx4 v[26:29], v[14:15], off nt
	v_pk_mul_f32 v[14:15], v[22:23], v[22:23]
	v_pk_fma_f32 v[46:47], v[46:47], v[46:47], v[76:77]
	v_pk_fma_f32 v[60:61], v[60:61], v[60:61], v[14:15]
	v_mov_b32_e32 v76, v46
	v_mov_b32_e32 v77, v42
	v_mov_b32_e32 v42, v47
	v_pk_add_f32 v[42:43], v[76:77], v[42:43]
	v_mov_b32_e32 v46, v49
	v_mov_b32_e32 v47, v61
	v_pk_add_f32 v[42:43], v[46:47], v[42:43]
	v_mov_b32_e32 v49, v60
	v_pk_add_f32 v[42:43], v[48:49], v[42:43]
	ds_bpermute_b32 v47, v41, v43
	ds_bpermute_b32 v46, v41, v42
	v_mov_b32_e32 v153, v147
	v_lshl_add_u64 v[54:55], v[12:13], 0, v[152:153]
	v_add_co_u32_e32 v12, vcc, s47, v16
	s_waitcnt lgkmcnt(0)
	v_pk_add_f32 v[42:43], v[42:43], v[46:47]
	ds_bpermute_b32 v47, v40, v43
	ds_bpermute_b32 v46, v40, v42
	v_addc_co_u32_e32 v13, vcc, 0, v17, vcc
	v_lshlrev_b32_e32 v39, 2, v24
	v_add_co_u32_e32 v62, vcc, s48, v16
	s_waitcnt lgkmcnt(0)
	v_pk_add_f32 v[42:43], v[42:43], v[46:47]
	v_addc_co_u32_e32 v63, vcc, 0, v17, vcc
	s_waitcnt vmcnt(5)
	v_lshlrev_b32_e32 v48, 16, v34
	v_and_b32_e32 v49, 0xffff0000, v34
	v_or_b32_e32 v34, s63, v160
	ds_bpermute_b32 v47, v39, v43
	ds_bpermute_b32 v46, v39, v42
	v_lshlrev_b32_e32 v38, 2, v25
	global_load_dwordx4 v[22:25], v[20:21], off nt
	s_nop 0
	global_load_dwordx4 v[18:21], v[12:13], off nt
	global_load_dwordx4 v[14:17], v[10:11], off nt
	s_nop 0
	global_load_dwordx4 v[10:13], v[62:63], off nt
	v_lshlrev_b32_e32 v62, 16, v37
	v_and_b32_e32 v63, 0xffff0000, v37
	v_lshlrev_b32_e32 v64, 16, v36
	v_and_b32_e32 v65, 0xffff0000, v36
	v_lshlrev_b32_e32 v36, 16, v35
	v_and_b32_e32 v37, 0xffff0000, v35
	v_ashrrev_i32_e32 v35, 31, v34
	v_lshlrev_b64 v[34:35], 11, v[34:35]
	v_lshl_add_u64 v[34:35], s[22:23], 0, v[34:35]
	v_lshl_add_u64 v[34:35], v[34:35], 0, s[26:27]
	v_lshl_add_u64 v[60:61], v[34:35], 0, v[152:153]
	s_waitcnt lgkmcnt(0)
	v_pk_add_f32 v[34:35], v[42:43], v[46:47]
	ds_bpermute_b32 v43, v38, v35
	ds_bpermute_b32 v42, v38, v34
	s_waitcnt vmcnt(6)
	v_lshlrev_b32_e32 v80, 16, v50
	v_and_b32_e32 v81, 0xffff0000, v50
	v_lshlrev_b32_e32 v76, 16, v53
	v_and_b32_e32 v77, 0xffff0000, v53
	s_waitcnt lgkmcnt(0)
	v_pk_add_f32 v[42:43], v[34:35], v[42:43]
	v_mov_b64_e32 v[34:35], s[36:37]
	v_pk_fma_f32 v[78:79], v[42:43], s[24:25], v[34:35] op_sel_hi:[1,0,0]
	v_lshlrev_b32_e32 v46, 16, v52
	v_mul_f32_e32 v42, 0x4b800000, v79
	v_cmp_gt_f32_e32 vcc, s49, v79
	v_and_b32_e32 v47, 0xffff0000, v52
	v_lshlrev_b32_e32 v52, 16, v51
	v_cndmask_b32_e32 v42, v79, v42, vcc
	v_rsq_f32_e32 v42, v42
	v_and_b32_e32 v53, 0xffff0000, v51
	v_readlane_b32 s4, v249, 2
	s_add_i32 s62, s62, s4
	v_mul_f32_e32 v43, 0x45800000, v42
	v_cndmask_b32_e32 v50, v42, v43, vcc
	v_pk_mul_f32 v[42:43], v[50:51], v[66:67] op_sel_hi:[0,1]
	v_pk_mul_f32 v[44:45], v[50:51], v[44:45] op_sel_hi:[0,1]
	v_pk_mul_f32 v[42:43], v[6:7], v[42:43]
	v_pk_mul_f32 v[44:45], v[8:9], v[44:45]
	v_pk_mul_f32 v[42:43], v[42:43], v[48:49]
	v_pk_mul_f32 v[36:37], v[44:45], v[36:37]
	v_cvt_pk_bf16_f32 v42, v42, v43
	v_cvt_pk_bf16_f32 v43, v36, v37
	v_pk_mul_f32 v[36:37], v[50:51], v[58:59] op_sel_hi:[0,1]
	v_mul_f32_e32 v45, 0x4b800000, v78
	v_cmp_gt_f32_e32 vcc, s49, v78
	v_pk_mul_f32 v[36:37], v[2:3], v[36:37]
	s_cmpk_lt_i32 s62, 0x200
	v_cndmask_b32_e32 v45, v78, v45, vcc
	v_pk_mul_f32 v[36:37], v[36:37], v[64:65]
	v_rsq_f32_e32 v48, v45
	v_cvt_pk_bf16_f32 v44, v36, v37
	v_pk_mul_f32 v[36:37], v[50:51], v[56:57] op_sel_hi:[0,1]
	v_pk_mul_f32 v[36:37], v[4:5], v[36:37]
	v_readlane_b32 s5, v249, 3
	v_pk_mul_f32 v[36:37], v[36:37], v[62:63]
	s_nop 0
	v_cvt_pk_bf16_f32 v45, v36, v37
	v_mul_f32_e32 v36, 0x45800000, v48
	v_cndmask_b32_e32 v36, v48, v36, vcc
	global_store_dwordx4 v[54:55], v[42:45], off
	s_nop 1
	v_pk_mul_f32 v[42:43], v[36:37], v[74:75] op_sel_hi:[0,1]
	v_pk_mul_f32 v[44:45], v[36:37], v[72:73] op_sel_hi:[0,1]
	v_pk_mul_f32 v[42:43], v[6:7], v[42:43]
	v_pk_mul_f32 v[44:45], v[8:9], v[44:45]
	v_pk_mul_f32 v[42:43], v[42:43], v[80:81]
	v_pk_mul_f32 v[44:45], v[44:45], v[52:53]
	v_cvt_pk_bf16_f32 v42, v42, v43
	v_cvt_pk_bf16_f32 v43, v44, v45
	v_pk_mul_f32 v[44:45], v[36:37], v[70:71] op_sel_hi:[0,1]
	v_pk_mul_f32 v[36:37], v[36:37], v[68:69] op_sel_hi:[0,1]
	v_pk_mul_f32 v[44:45], v[2:3], v[44:45]
	v_pk_mul_f32 v[36:37], v[4:5], v[36:37]
	v_pk_mul_f32 v[44:45], v[44:45], v[46:47]
	v_pk_mul_f32 v[36:37], v[36:37], v[76:77]
	v_cvt_pk_bf16_f32 v44, v44, v45
	v_cvt_pk_bf16_f32 v45, v36, v37
	global_store_dwordx4 v[60:61], v[42:45], off
	ds_read_b128 v[42:45], v172
	ds_read_b128 v[46:49], v173
	s_waitcnt vmcnt(6)
	v_lshlrev_b32_e32 v72, 16, v27
	v_and_b32_e32 v73, 0xffff0000, v27
	v_lshlrev_b32_e32 v52, 16, v33
	s_waitcnt lgkmcnt(1)
	v_and_b32_e32 v51, 0xffff0000, v45
	v_and_b32_e32 v55, 0xffff0000, v44
	v_lshlrev_b32_e32 v50, 16, v45
	v_lshlrev_b32_e32 v54, 16, v44
	v_mov_b32_e32 v58, v51
	v_mov_b32_e32 v59, v55
	v_mov_b32_e32 v56, v50
	v_mov_b32_e32 v57, v54
	v_pk_mul_f32 v[58:59], v[58:59], v[58:59]
	v_and_b32_e32 v61, 0xffff0000, v42
	v_pk_fma_f32 v[56:57], v[56:57], v[56:57], v[58:59]
	v_and_b32_e32 v59, 0xffff0000, v43
	v_lshlrev_b32_e32 v58, 16, v43
	v_lshlrev_b32_e32 v60, 16, v42
	v_mov_b32_e32 v62, v61
	v_mov_b32_e32 v63, v59
	v_mov_b32_e32 v42, v60
	v_mov_b32_e32 v43, v58
	v_pk_mul_f32 v[62:63], v[62:63], v[62:63]
	s_waitcnt lgkmcnt(0)
	v_and_b32_e32 v65, 0xffff0000, v48
	v_pk_fma_f32 v[42:43], v[42:43], v[42:43], v[62:63]
	v_and_b32_e32 v63, 0xffff0000, v49
	v_lshlrev_b32_e32 v62, 16, v49
	v_lshlrev_b32_e32 v64, 16, v48
	v_mov_b32_e32 v66, v63
	v_mov_b32_e32 v67, v65
	v_mov_b32_e32 v48, v62
	v_mov_b32_e32 v49, v64
	v_pk_mul_f32 v[66:67], v[66:67], v[66:67]
	v_and_b32_e32 v69, 0xffff0000, v46
	v_pk_fma_f32 v[48:49], v[48:49], v[48:49], v[66:67]
	v_and_b32_e32 v67, 0xffff0000, v47
	v_lshlrev_b32_e32 v66, 16, v47
	v_lshlrev_b32_e32 v68, 16, v46
	v_mov_b32_e32 v70, v69
	v_mov_b32_e32 v71, v67
	v_mov_b32_e32 v46, v68
	v_mov_b32_e32 v47, v66
	v_pk_mul_f32 v[70:71], v[70:71], v[70:71]
	v_and_b32_e32 v53, 0xffff0000, v33
	v_pk_fma_f32 v[46:47], v[46:47], v[46:47], v[70:71]
	v_mov_b32_e32 v71, v42
	v_mov_b32_e32 v70, v46
	v_mov_b32_e32 v42, v47
	v_pk_add_f32 v[42:43], v[70:71], v[42:43]
	v_mov_b32_e32 v46, v49
	v_mov_b32_e32 v47, v57
	v_pk_add_f32 v[42:43], v[46:47], v[42:43]
	v_mov_b32_e32 v49, v56
	v_pk_add_f32 v[42:43], v[48:49], v[42:43]
	ds_bpermute_b32 v47, v41, v43
	ds_bpermute_b32 v46, v41, v42
	v_lshlrev_b32_e32 v56, 16, v29
	v_and_b32_e32 v57, 0xffff0000, v29
	v_lshlrev_b32_e32 v70, 16, v28
	v_and_b32_e32 v71, 0xffff0000, v28
	s_waitcnt lgkmcnt(0)
	v_pk_add_f32 v[42:43], v[42:43], v[46:47]
	ds_bpermute_b32 v47, v40, v43
	ds_bpermute_b32 v46, v40, v42
	v_lshlrev_b32_e32 v44, 16, v32
	v_and_b32_e32 v45, 0xffff0000, v32
	v_lshlrev_b32_e32 v32, 16, v31
	v_and_b32_e32 v33, 0xffff0000, v31
	s_waitcnt lgkmcnt(0)
	v_pk_add_f32 v[42:43], v[42:43], v[46:47]
	ds_bpermute_b32 v47, v39, v43
	ds_bpermute_b32 v46, v39, v42
	v_lshlrev_b32_e32 v48, 16, v30
	v_and_b32_e32 v49, 0xffff0000, v30
	v_or_b32_e32 v36, s63, v161
	v_ashrrev_i32_e32 v37, 31, v36
	s_waitcnt lgkmcnt(0)
	v_pk_add_f32 v[42:43], v[42:43], v[46:47]
	ds_bpermute_b32 v47, v38, v43
	ds_bpermute_b32 v46, v38, v42
	v_lshlrev_b64 v[36:37], 11, v[36:37]
	v_lshl_add_u64 v[36:37], s[22:23], 0, v[36:37]
	v_lshl_add_u64 v[36:37], v[36:37], 0, s[26:27]
	v_lshl_add_u64 v[36:37], v[36:37], 0, v[152:153]
	s_waitcnt lgkmcnt(0)
	v_pk_add_f32 v[28:29], v[42:43], v[46:47]
	v_lshlrev_b32_e32 v46, 16, v26
	v_pk_fma_f32 v[42:43], v[28:29], s[24:25], v[34:35] op_sel_hi:[1,0,0]
	v_and_b32_e32 v47, 0xffff0000, v26
	v_mul_f32_e32 v28, 0x4b800000, v43
	v_cmp_gt_f32_e32 vcc, s49, v43
	v_or_b32_e32 v30, s63, v162
	v_ashrrev_i32_e32 v31, 31, v30
	v_cndmask_b32_e32 v28, v43, v28, vcc
	v_rsq_f32_e32 v28, v28
	v_lshlrev_b64 v[30:31], 11, v[30:31]
	v_lshl_add_u64 v[30:31], s[22:23], 0, v[30:31]
	v_lshl_add_u64 v[30:31], v[30:31], 0, s[26:27]
	v_mul_f32_e32 v26, 0x45800000, v28
	v_cndmask_b32_e32 v74, v28, v26, vcc
	v_pk_mul_f32 v[26:27], v[74:75], v[60:61] op_sel_hi:[0,1]
	v_pk_mul_f32 v[28:29], v[74:75], v[58:59] op_sel_hi:[0,1]
	v_pk_mul_f32 v[26:27], v[6:7], v[26:27]
	v_pk_mul_f32 v[28:29], v[8:9], v[28:29]
	v_pk_mul_f32 v[26:27], v[26:27], v[48:49]
	v_pk_mul_f32 v[28:29], v[28:29], v[32:33]
	v_cvt_pk_bf16_f32 v26, v26, v27
	v_cvt_pk_bf16_f32 v27, v28, v29
	v_pk_mul_f32 v[28:29], v[74:75], v[54:55] op_sel_hi:[0,1]
	v_pk_mul_f32 v[28:29], v[2:3], v[28:29]
	v_cmp_gt_f32_e32 vcc, s49, v42
	v_pk_mul_f32 v[28:29], v[28:29], v[44:45]
	v_pk_mul_f32 v[32:33], v[74:75], v[50:51] op_sel_hi:[0,1]
	v_cvt_pk_bf16_f32 v28, v28, v29
	v_mul_f32_e32 v29, 0x4b800000, v42
	v_cndmask_b32_e32 v29, v42, v29, vcc
	v_rsq_f32_e32 v42, v29
	v_pk_mul_f32 v[32:33], v[4:5], v[32:33]
	v_lshl_add_u64 v[30:31], v[30:31], 0, v[152:153]
	v_pk_mul_f32 v[32:33], v[32:33], v[52:53]
	s_waitcnt vmcnt(5)
	v_lshlrev_b32_e32 v44, 16, v25
	v_cvt_pk_bf16_f32 v29, v32, v33
	global_store_dwordx4 v[36:37], v[26:29], off
	v_and_b32_e32 v45, 0xffff0000, v25
	v_and_b32_e32 v25, 0xffff0000, v23
	v_mul_f32_e32 v26, 0x45800000, v42
	v_cndmask_b32_e32 v32, v42, v26, vcc
	v_pk_mul_f32 v[26:27], v[32:33], v[68:69] op_sel_hi:[0,1]
	v_pk_mul_f32 v[28:29], v[32:33], v[66:67] op_sel_hi:[0,1]
	v_pk_mul_f32 v[26:27], v[6:7], v[26:27]
	v_pk_mul_f32 v[28:29], v[8:9], v[28:29]
	v_pk_mul_f32 v[26:27], v[26:27], v[46:47]
	v_pk_mul_f32 v[28:29], v[28:29], v[72:73]
	v_cvt_pk_bf16_f32 v26, v26, v27
	v_cvt_pk_bf16_f32 v27, v28, v29
	v_pk_mul_f32 v[28:29], v[32:33], v[64:65] op_sel_hi:[0,1]
	v_pk_mul_f32 v[32:33], v[32:33], v[62:63] op_sel_hi:[0,1]
	v_pk_mul_f32 v[28:29], v[2:3], v[28:29]
	v_pk_mul_f32 v[32:33], v[4:5], v[32:33]
	v_pk_mul_f32 v[28:29], v[28:29], v[70:71]
	v_pk_mul_f32 v[32:33], v[32:33], v[56:57]
	v_cvt_pk_bf16_f32 v28, v28, v29
	v_cvt_pk_bf16_f32 v29, v32, v33
	global_store_dwordx4 v[30:31], v[26:29], off
	ds_read_b128 v[26:29], v174
	v_or_b32_e32 v30, s63, v163
	v_ashrrev_i32_e32 v31, 31, v30
	v_lshlrev_b64 v[30:31], 11, v[30:31]
	v_lshl_add_u64 v[30:31], s[22:23], 0, v[30:31]
	v_lshl_add_u64 v[30:31], v[30:31], 0, s[26:27]
	v_lshl_add_u64 v[36:37], v[30:31], 0, v[152:153]
	ds_read_b128 v[30:33], v175
	s_waitcnt lgkmcnt(1)
	v_and_b32_e32 v43, 0xffff0000, v29
	v_and_b32_e32 v47, 0xffff0000, v28
	v_lshlrev_b32_e32 v42, 16, v29
	v_lshlrev_b32_e32 v46, 16, v28
	v_mov_b32_e32 v50, v43
	v_mov_b32_e32 v51, v47
	v_mov_b32_e32 v48, v42
	v_mov_b32_e32 v49, v46
	v_pk_mul_f32 v[50:51], v[50:51], v[50:51]
	v_and_b32_e32 v53, 0xffff0000, v26
	v_pk_fma_f32 v[48:49], v[48:49], v[48:49], v[50:51]
	v_and_b32_e32 v51, 0xffff0000, v27
	v_lshlrev_b32_e32 v50, 16, v27
	v_lshlrev_b32_e32 v52, 16, v26
	v_mov_b32_e32 v54, v53
	v_mov_b32_e32 v55, v51
	v_mov_b32_e32 v26, v52
	v_mov_b32_e32 v27, v50
	v_pk_mul_f32 v[54:55], v[54:55], v[54:55]
	s_waitcnt lgkmcnt(0)
	v_and_b32_e32 v57, 0xffff0000, v32
	v_pk_fma_f32 v[26:27], v[26:27], v[26:27], v[54:55]
	v_and_b32_e32 v55, 0xffff0000, v33
	v_lshlrev_b32_e32 v54, 16, v33
	v_lshlrev_b32_e32 v56, 16, v32
	v_mov_b32_e32 v58, v55
	v_mov_b32_e32 v59, v57
	v_mov_b32_e32 v32, v54
	v_mov_b32_e32 v33, v56
	v_pk_mul_f32 v[58:59], v[58:59], v[58:59]
	v_and_b32_e32 v61, 0xffff0000, v30
	v_pk_fma_f32 v[32:33], v[32:33], v[32:33], v[58:59]
	v_and_b32_e32 v59, 0xffff0000, v31
	v_lshlrev_b32_e32 v58, 16, v31
	v_lshlrev_b32_e32 v60, 16, v30
	v_mov_b32_e32 v62, v61
	v_mov_b32_e32 v63, v59
	v_mov_b32_e32 v30, v60
	v_mov_b32_e32 v31, v58
	v_pk_mul_f32 v[62:63], v[62:63], v[62:63]
	s_waitcnt vmcnt(6)
	v_lshlrev_b32_e32 v64, 16, v19
	v_pk_fma_f32 v[30:31], v[30:31], v[30:31], v[62:63]
	v_mov_b32_e32 v63, v26
	v_mov_b32_e32 v62, v30
	v_mov_b32_e32 v26, v31
	v_pk_add_f32 v[26:27], v[62:63], v[26:27]
	v_mov_b32_e32 v30, v33
	v_mov_b32_e32 v31, v49
	v_pk_add_f32 v[26:27], v[30:31], v[26:27]
	v_mov_b32_e32 v33, v48
	v_pk_add_f32 v[26:27], v[32:33], v[26:27]
	ds_bpermute_b32 v31, v41, v27
	ds_bpermute_b32 v30, v41, v26
	v_lshlrev_b32_e32 v48, 16, v21
	v_and_b32_e32 v49, 0xffff0000, v21
	v_lshlrev_b32_e32 v62, 16, v20
	v_and_b32_e32 v63, 0xffff0000, v20
	s_waitcnt lgkmcnt(0)
	v_pk_add_f32 v[26:27], v[26:27], v[30:31]
	ds_bpermute_b32 v31, v40, v27
	ds_bpermute_b32 v30, v40, v26
	v_and_b32_e32 v65, 0xffff0000, v19
	v_lshlrev_b32_e32 v28, 16, v24
	v_and_b32_e32 v29, 0xffff0000, v24
	v_lshlrev_b32_e32 v24, 16, v23
	s_waitcnt lgkmcnt(0)
	v_pk_add_f32 v[26:27], v[26:27], v[30:31]
	ds_bpermute_b32 v31, v39, v27
	ds_bpermute_b32 v30, v39, v26
	v_lshlrev_b32_e32 v32, 16, v22
	v_and_b32_e32 v33, 0xffff0000, v22
	v_or_b32_e32 v22, s63, v164
	v_ashrrev_i32_e32 v23, 31, v22
	s_waitcnt lgkmcnt(0)
	v_pk_add_f32 v[26:27], v[26:27], v[30:31]
	ds_bpermute_b32 v31, v38, v27
	ds_bpermute_b32 v30, v38, v26
	v_lshlrev_b64 v[22:23], 11, v[22:23]
	v_lshl_add_u64 v[22:23], s[22:23], 0, v[22:23]
	v_lshl_add_u64 v[22:23], v[22:23], 0, s[26:27]
	v_lshl_add_u64 v[22:23], v[22:23], 0, v[152:153]
	s_waitcnt lgkmcnt(0)
	v_pk_add_f32 v[20:21], v[26:27], v[30:31]
	v_lshlrev_b32_e32 v30, 16, v18
	v_pk_fma_f32 v[26:27], v[20:21], s[24:25], v[34:35] op_sel_hi:[1,0,0]
	v_and_b32_e32 v31, 0xffff0000, v18
	v_mul_f32_e32 v20, 0x4b800000, v27
	v_cmp_gt_f32_e32 vcc, s49, v27
	s_nop 1
	v_cndmask_b32_e32 v20, v27, v20, vcc
	v_rsq_f32_e32 v20, v20
	s_nop 0
	v_mul_f32_e32 v18, 0x45800000, v20
	v_cndmask_b32_e32 v66, v20, v18, vcc
	v_pk_mul_f32 v[18:19], v[66:67], v[52:53] op_sel_hi:[0,1]
	v_pk_mul_f32 v[20:21], v[66:67], v[50:51] op_sel_hi:[0,1]
	v_pk_mul_f32 v[18:19], v[6:7], v[18:19]
	v_pk_mul_f32 v[20:21], v[8:9], v[20:21]
	v_pk_mul_f32 v[18:19], v[18:19], v[32:33]
	v_pk_mul_f32 v[20:21], v[20:21], v[24:25]
	v_cvt_pk_bf16_f32 v18, v18, v19
	v_cvt_pk_bf16_f32 v19, v20, v21
	v_pk_mul_f32 v[20:21], v[66:67], v[46:47] op_sel_hi:[0,1]
	v_pk_mul_f32 v[20:21], v[2:3], v[20:21]
	v_cmp_gt_f32_e32 vcc, s49, v26
	v_pk_mul_f32 v[20:21], v[20:21], v[28:29]
	v_pk_mul_f32 v[24:25], v[66:67], v[42:43] op_sel_hi:[0,1]
	v_cvt_pk_bf16_f32 v20, v20, v21
	v_mul_f32_e32 v21, 0x4b800000, v26
	v_cndmask_b32_e32 v21, v26, v21, vcc
	v_rsq_f32_e32 v26, v21
	v_pk_mul_f32 v[24:25], v[4:5], v[24:25]
	s_nop 0
	v_pk_mul_f32 v[24:25], v[24:25], v[44:45]
	s_nop 0
	v_cvt_pk_bf16_f32 v21, v24, v25
	global_store_dwordx4 v[36:37], v[18:21], off
	s_nop 1
	v_mul_f32_e32 v18, 0x45800000, v26
	v_cndmask_b32_e32 v24, v26, v18, vcc
	v_pk_mul_f32 v[18:19], v[24:25], v[60:61] op_sel_hi:[0,1]
	v_pk_mul_f32 v[20:21], v[24:25], v[58:59] op_sel_hi:[0,1]
	v_pk_mul_f32 v[18:19], v[6:7], v[18:19]
	v_pk_mul_f32 v[20:21], v[8:9], v[20:21]
	v_pk_mul_f32 v[18:19], v[18:19], v[30:31]
	v_pk_mul_f32 v[20:21], v[20:21], v[64:65]
	v_cvt_pk_bf16_f32 v18, v18, v19
	v_cvt_pk_bf16_f32 v19, v20, v21
	v_pk_mul_f32 v[20:21], v[24:25], v[56:57] op_sel_hi:[0,1]
	v_pk_mul_f32 v[24:25], v[24:25], v[54:55] op_sel_hi:[0,1]
	v_pk_mul_f32 v[20:21], v[2:3], v[20:21]
	v_pk_mul_f32 v[24:25], v[4:5], v[24:25]
	v_pk_mul_f32 v[20:21], v[20:21], v[62:63]
	v_pk_mul_f32 v[24:25], v[24:25], v[48:49]
	v_cvt_pk_bf16_f32 v20, v20, v21
	v_cvt_pk_bf16_f32 v21, v24, v25
	global_store_dwordx4 v[22:23], v[18:21], off
	ds_read_b128 v[18:21], v176
	v_or_b32_e32 v22, s63, v165
	v_ashrrev_i32_e32 v23, 31, v22
	v_lshlrev_b64 v[22:23], 11, v[22:23]
	v_lshl_add_u64 v[22:23], s[22:23], 0, v[22:23]
	v_lshl_add_u64 v[22:23], v[22:23], 0, s[26:27]
	v_lshl_add_u64 v[26:27], v[22:23], 0, v[152:153]
	ds_read_b128 v[22:25], v177
	s_waitcnt lgkmcnt(1)
	v_and_b32_e32 v29, 0xffff0000, v21
	v_and_b32_e32 v33, 0xffff0000, v20
	v_lshlrev_b32_e32 v28, 16, v21
	v_lshlrev_b32_e32 v32, 16, v20
	v_mov_b32_e32 v42, v29
	v_mov_b32_e32 v43, v33
	v_mov_b32_e32 v36, v28
	v_mov_b32_e32 v37, v32
	v_pk_mul_f32 v[42:43], v[42:43], v[42:43]
	v_and_b32_e32 v45, 0xffff0000, v18
	v_pk_fma_f32 v[36:37], v[36:37], v[36:37], v[42:43]
	v_and_b32_e32 v43, 0xffff0000, v19
	v_lshlrev_b32_e32 v42, 16, v19
	v_lshlrev_b32_e32 v44, 16, v18
	v_mov_b32_e32 v46, v45
	v_mov_b32_e32 v47, v43
	v_mov_b32_e32 v18, v44
	v_mov_b32_e32 v19, v42
	v_pk_mul_f32 v[46:47], v[46:47], v[46:47]
	s_waitcnt lgkmcnt(0)
	v_and_b32_e32 v49, 0xffff0000, v24
	v_pk_fma_f32 v[18:19], v[18:19], v[18:19], v[46:47]
	v_and_b32_e32 v47, 0xffff0000, v25
	v_lshlrev_b32_e32 v46, 16, v25
	v_lshlrev_b32_e32 v48, 16, v24
	v_mov_b32_e32 v50, v47
	v_mov_b32_e32 v51, v49
	v_mov_b32_e32 v24, v46
	v_mov_b32_e32 v25, v48
	v_pk_mul_f32 v[50:51], v[50:51], v[50:51]
	v_and_b32_e32 v53, 0xffff0000, v22
	v_pk_fma_f32 v[24:25], v[24:25], v[24:25], v[50:51]
	v_and_b32_e32 v51, 0xffff0000, v23
	v_lshlrev_b32_e32 v50, 16, v23
	v_lshlrev_b32_e32 v52, 16, v22
	v_mov_b32_e32 v54, v53
	v_mov_b32_e32 v55, v51
	v_mov_b32_e32 v22, v52
	v_mov_b32_e32 v23, v50
	v_pk_mul_f32 v[54:55], v[54:55], v[54:55]
	s_waitcnt vmcnt(7)
	v_lshlrev_b32_e32 v30, 16, v17
	v_pk_fma_f32 v[22:23], v[22:23], v[22:23], v[54:55]
	v_mov_b32_e32 v55, v18
	v_mov_b32_e32 v54, v22
	v_mov_b32_e32 v18, v23
	v_pk_add_f32 v[18:19], v[54:55], v[18:19]
	v_mov_b32_e32 v22, v25
	v_mov_b32_e32 v23, v37
	v_pk_add_f32 v[18:19], v[22:23], v[18:19]
	v_mov_b32_e32 v25, v36
	v_pk_add_f32 v[18:19], v[24:25], v[18:19]
	ds_bpermute_b32 v23, v41, v19
	ds_bpermute_b32 v22, v41, v18
	s_waitcnt vmcnt(6)
	v_lshlrev_b32_e32 v36, 16, v13
	v_and_b32_e32 v37, 0xffff0000, v13
	v_and_b32_e32 v41, 0xffff0000, v11
	v_and_b32_e32 v31, 0xffff0000, v17
	s_waitcnt lgkmcnt(0)
	v_pk_add_f32 v[18:19], v[18:19], v[22:23]
	ds_bpermute_b32 v23, v40, v19
	ds_bpermute_b32 v22, v40, v18
	v_lshlrev_b32_e32 v40, 16, v11
	v_lshlrev_b32_e32 v20, 16, v16
	v_and_b32_e32 v21, 0xffff0000, v16
	v_lshlrev_b32_e32 v16, 16, v15
	s_waitcnt lgkmcnt(0)
	v_pk_add_f32 v[18:19], v[18:19], v[22:23]
	ds_bpermute_b32 v23, v39, v19
	ds_bpermute_b32 v22, v39, v18
	v_and_b32_e32 v39, 0xffff0000, v12
	v_and_b32_e32 v17, 0xffff0000, v15
	v_lshlrev_b32_e32 v24, 16, v14
	v_and_b32_e32 v25, 0xffff0000, v14
	s_waitcnt lgkmcnt(0)
	v_pk_add_f32 v[18:19], v[18:19], v[22:23]
	ds_bpermute_b32 v23, v38, v19
	ds_bpermute_b32 v22, v38, v18
	v_lshlrev_b32_e32 v38, 16, v12
	v_add_u32_e32 v14, s63, v166
	v_ashrrev_i32_e32 v15, 31, v14
	v_lshlrev_b64 v[14:15], 11, v[14:15]
	s_waitcnt lgkmcnt(0)
	v_pk_add_f32 v[12:13], v[18:19], v[22:23]
	v_lshlrev_b32_e32 v22, 16, v10
	v_pk_fma_f32 v[18:19], v[12:13], s[24:25], v[34:35] op_sel_hi:[1,0,0]
	v_and_b32_e32 v23, 0xffff0000, v10
	v_mul_f32_e32 v12, 0x4b800000, v19
	v_cmp_gt_f32_e32 vcc, s49, v19
	v_lshl_add_u64 v[14:15], s[22:23], 0, v[14:15]
	v_lshl_add_u64 v[14:15], v[14:15], 0, s[26:27]
	v_cndmask_b32_e32 v12, v19, v12, vcc
	v_rsq_f32_e32 v12, v12
	v_lshl_add_u64 v[14:15], v[14:15], 0, v[152:153]
	v_mul_f32_e32 v10, 0x45800000, v12
	v_cndmask_b32_e32 v34, v12, v10, vcc
	v_pk_mul_f32 v[10:11], v[34:35], v[44:45] op_sel_hi:[0,1]
	v_pk_mul_f32 v[12:13], v[34:35], v[42:43] op_sel_hi:[0,1]
	v_pk_mul_f32 v[10:11], v[6:7], v[10:11]
	v_pk_mul_f32 v[12:13], v[8:9], v[12:13]
	v_pk_mul_f32 v[10:11], v[10:11], v[24:25]
	v_pk_mul_f32 v[12:13], v[12:13], v[16:17]
	v_cvt_pk_bf16_f32 v10, v10, v11
	v_cvt_pk_bf16_f32 v11, v12, v13
	v_pk_mul_f32 v[12:13], v[34:35], v[32:33] op_sel_hi:[0,1]
	v_pk_mul_f32 v[12:13], v[2:3], v[12:13]
	v_cmp_gt_f32_e32 vcc, s49, v18
	v_pk_mul_f32 v[12:13], v[12:13], v[20:21]
	v_pk_mul_f32 v[16:17], v[34:35], v[28:29] op_sel_hi:[0,1]
	v_cvt_pk_bf16_f32 v12, v12, v13
	v_mul_f32_e32 v13, 0x4b800000, v18
	v_cndmask_b32_e32 v13, v18, v13, vcc
	v_rsq_f32_e32 v18, v13
	v_pk_mul_f32 v[16:17], v[4:5], v[16:17]
	s_nop 0
	v_pk_mul_f32 v[16:17], v[16:17], v[30:31]
	s_nop 0
	v_cvt_pk_bf16_f32 v13, v16, v17
	global_store_dwordx4 v[26:27], v[10:13], off
	s_nop 1
	v_mul_f32_e32 v10, 0x45800000, v18
	v_cndmask_b32_e32 v10, v18, v10, vcc
	v_pk_mul_f32 v[12:13], v[10:11], v[52:53] op_sel_hi:[0,1]
	v_pk_mul_f32 v[6:7], v[6:7], v[12:13]
	v_pk_mul_f32 v[12:13], v[10:11], v[50:51] op_sel_hi:[0,1]
	v_pk_mul_f32 v[8:9], v[8:9], v[12:13]
	v_pk_mul_f32 v[6:7], v[6:7], v[22:23]
	v_pk_mul_f32 v[8:9], v[8:9], v[40:41]
	v_cvt_pk_bf16_f32 v6, v6, v7
	v_cvt_pk_bf16_f32 v7, v8, v9
	v_pk_mul_f32 v[8:9], v[10:11], v[48:49] op_sel_hi:[0,1]
	v_pk_mul_f32 v[2:3], v[2:3], v[8:9]
	s_nop 0
	v_pk_mul_f32 v[2:3], v[2:3], v[38:39]
	s_nop 0
	v_cvt_pk_bf16_f32 v8, v2, v3
	v_pk_mul_f32 v[2:3], v[10:11], v[46:47] op_sel_hi:[0,1]
	v_pk_mul_f32 v[2:3], v[4:5], v[2:3]
	s_nop 0
	v_pk_mul_f32 v[2:3], v[2:3], v[36:37]
	s_nop 0
	v_cvt_pk_bf16_f32 v9, v2, v3
	global_store_dwordx4 v[14:15], v[6:9], off
	s_barrier
	s_cbranch_scc0 .LBB0_1346
.LBB0_1332:
	s_and_b32 s4, s62, 15
	s_ashr_i32 s5, s62, 7
	s_lshl_b32 s6, s5, 12
	s_lshl_b32 s7, s4, 8
	s_or_b32 s63, s6, s7
	s_lshl_b32 s8, s5, 3
	s_lshl_b32 s9, s4, 15
	v_readfirstlane_b32 s4, v0
	s_bfe_u32 s2, s62, 0x30004
	s_addk_i32 s63, 0x1000
	s_add_i32 s11, s8, 32
	s_lshr_b32 s14, s4, 8
	s_bfe_u32 s10, s4, 0x20006
	s_cmpk_lt_u32 s4, 0x100
	s_cselect_b64 s[4:5], -1, 0
	s_and_b64 s[6:7], s[4:5], exec
	s_cselect_b32 s6, s8, s11
	s_or_b32 s6, s6, s2
	s_ashr_i32 s7, s6, 31
	s_lshl_b64 s[6:7], s[6:7], 19
	s_add_u32 s6, s96, s6
	s_addc_u32 s7, s97, s7
	s_add_u32 s8, s6, s9
	s_addc_u32 s9, s7, 0
	s_and_b64 s[6:7], s[4:5], exec
	s_cselect_b32 s7, s35, s51
	s_cselect_b32 s6, s3, s50
	s_lshl_b32 s26, s10, 8
	v_mbcnt_lo_u32_b32 v2, -1, 0
	v_mbcnt_hi_u32_b32 v2, -1, v2
	s_or_b32 s12, s26, 64
	v_ashrrev_i32_e32 v3, 31, v2
	v_lshl_add_u64 v[2:3], s[26:27], 0, v[2:3]
	v_lshlrev_b64 v[2:3], 5, v[2:3]
	v_lshl_add_u64 v[2:3], s[8:9], 0, v[2:3]
	global_load_dwordx4 v[6:9], v[2:3], off nt
	global_load_dwordx4 v[14:17], v[2:3], off offset:16 nt
	v_mbcnt_lo_u32_b32 v2, -1, 0
	v_mbcnt_hi_u32_b32 v2, -1, v2
	s_mov_b32 s13, s27
	v_ashrrev_i32_e32 v3, 31, v2
	v_lshl_add_u64 v[2:3], v[2:3], 0, s[12:13]
	v_lshlrev_b64 v[2:3], 5, v[2:3]
	v_lshl_add_u64 v[2:3], s[8:9], 0, v[2:3]
	global_load_dwordx4 v[22:25], v[2:3], off nt
	global_load_dwordx4 v[30:33], v[2:3], off offset:16 nt
	s_or_b32 s12, s26, 0x80
	v_mbcnt_lo_u32_b32 v2, -1, 0
	v_mbcnt_hi_u32_b32 v2, -1, v2
	s_or_b32 s26, s26, 0xc0
	v_ashrrev_i32_e32 v3, 31, v2
	v_lshl_add_u64 v[2:3], v[2:3], 0, s[12:13]
	v_lshlrev_b64 v[2:3], 5, v[2:3]
	v_lshl_add_u64 v[2:3], s[8:9], 0, v[2:3]
	global_load_dwordx4 v[38:41], v[2:3], off nt
	global_load_dwordx4 v[46:49], v[2:3], off offset:16 nt
	v_mbcnt_lo_u32_b32 v2, -1, 0
	v_mbcnt_hi_u32_b32 v2, -1, v2
	s_mov_b32 s19, s27
	v_ashrrev_i32_e32 v3, 31, v2
	v_lshl_add_u64 v[2:3], v[2:3], 0, s[26:27]
	v_lshlrev_b64 v[2:3], 5, v[2:3]
	v_lshl_add_u64 v[2:3], s[8:9], 0, v[2:3]
	global_load_dwordx4 v[54:57], v[2:3], off nt
	global_load_dwordx4 v[62:65], v[2:3], off offset:16 nt
	s_waitcnt vmcnt(0)
	v_mbcnt_lo_u32_b32 v68, -1, 0
	v_mbcnt_hi_u32_b32 v68, -1, v68
	s_lshl_b32 s26, s2, 8
	v_lshl_add_u32 v66, s10, 6, v68
	v_ashrrev_i32_e32 v71, 3, v66
	v_ashrrev_i32_e32 v73, 5, v68
	v_and_b32_e32 v72, 31, v68
	v_sub_u32_e32 v67, 31, v71
	v_lshlrev_b32_e32 v77, 2, v73
	v_cndmask_b32_e64 v75, v67, v71, s[4:5]
	v_lshlrev_b32_e32 v67, 5, v68
	v_cmp_gt_i32_e32 vcc, v77, v72
	v_and_b32_e32 v76, 0xe0, v67
	v_and_b32_e32 v153, 15, v68
	v_cndmask_b32_e64 v67, v167, 0, vcc
	v_cmp_lt_i32_e32 vcc, v77, v72
	v_ashrrev_i32_e32 v70, 4, v68
	v_lshl_or_b32 v69, s10, 4, v153
	v_cndmask_b32_e32 v78, 0, v168, vcc
	v_or_b32_e32 v178, v67, v78
	v_or_b32_e32 v67, 2, v77
	v_cmp_gt_i32_e32 vcc, v67, v72
	v_sub_u32_e32 v66, 3, v70
	v_cndmask_b32_e64 v66, v66, v70, s[4:5]
	v_cndmask_b32_e64 v78, v167, 0, vcc
	v_cmp_lt_i32_e32 vcc, v67, v72
	v_lshlrev_b32_e32 v74, 2, v69
	v_lshl_or_b32 v146, v66, 14, v74
	v_cndmask_b32_e32 v67, 0, v168, vcc
	v_or_b32_e32 v179, v78, v67
	v_add_u32_e32 v67, 8, v77
	v_cmp_gt_i32_e32 vcc, v67, v72
	v_lshl_add_u64 v[156:157], s[6:7], 0, v[146:147]
	s_and_b64 s[6:7], s[4:5], exec
	v_cndmask_b32_e64 v78, v167, 0, vcc
	v_cmp_lt_i32_e32 vcc, v67, v72
	s_cselect_b32 s2, 0, 0xe7
	s_or_b32 s6, s63, s2
	v_cndmask_b32_e32 v67, 0, v168, vcc
	v_or_b32_e32 v180, v78, v67
	v_add_u32_e32 v67, 10, v77
	v_cmp_gt_i32_e32 vcc, v67, v72
	s_ashr_i32 s7, s6, 31
	s_lshl_b64 s[6:7], s[6:7], 11
	v_cndmask_b32_e64 v78, v167, 0, vcc
	v_cmp_lt_i32_e32 vcc, v67, v72
	v_lshl_add_u64 v[154:155], s[0:1], 0, v[146:147]
	s_or_b32 s6, s6, s26
	v_cndmask_b32_e32 v67, 0, v168, vcc
	v_or_b32_e32 v181, v78, v67
	v_add_u32_e32 v67, 16, v77
	v_cmp_gt_i32_e32 vcc, v67, v72
	s_mul_i32 s8, s14, 0xb700
	v_lshl_or_b32 v146, v75, 11, v76
	v_cndmask_b32_e64 v78, v167, 0, vcc
	v_cmp_lt_i32_e32 vcc, v67, v72
	v_lshlrev_b32_e32 v80, 2, v68
	v_sub_u32_e32 v83, 31, v77
	v_cndmask_b32_e32 v67, 0, v168, vcc
	v_or_b32_e32 v182, v78, v67
	v_lshl_add_u64 v[66:67], v[154:155], 0, s[6:7]
	global_load_dword v183, v[66:67], off nt
	v_lshl_add_u64 v[66:67], v[156:157], 0, s[6:7]
	s_and_b64 s[6:7], s[4:5], exec
	s_cselect_b32 s2, 1, 0xe6
	s_or_b32 s6, s63, s2
	s_ashr_i32 s7, s6, 31
	s_lshl_b64 s[6:7], s[6:7], 11
	s_or_b32 s6, s6, s26
	global_load_dword v184, v[66:67], off nt
	v_lshl_add_u64 v[66:67], v[154:155], 0, s[6:7]
	global_load_dword v185, v[66:67], off nt
	v_lshl_add_u64 v[66:67], v[156:157], 0, s[6:7]
	s_and_b64 s[6:7], s[4:5], exec
	s_cselect_b32 s2, 2, 0xe5
	s_or_b32 s6, s63, s2
	s_ashr_i32 s7, s6, 31
	s_lshl_b64 s[6:7], s[6:7], 11
	s_or_b32 s6, s6, s26
	global_load_dword v186, v[66:67], off nt
	v_lshl_add_u64 v[66:67], v[154:155], 0, s[6:7]
	global_load_dword v187, v[66:67], off nt
	v_lshl_add_u64 v[66:67], v[156:157], 0, s[6:7]
	s_and_b64 s[6:7], s[4:5], exec
	s_cselect_b32 s2, 3, 0xe4
	s_or_b32 s6, s63, s2
	s_ashr_i32 s7, s6, 31
	s_lshl_b64 s[6:7], s[6:7], 11
	s_or_b32 s6, s6, s26
	global_load_dword v188, v[66:67], off nt
	v_lshl_add_u64 v[66:67], v[154:155], 0, s[6:7]
	global_load_dword v189, v[66:67], off nt
	v_lshl_add_u64 v[66:67], v[156:157], 0, s[6:7]
	s_and_b64 s[6:7], s[4:5], exec
	s_cselect_b32 s2, 4, 0xe3
	s_or_b32 s6, s63, s2
	s_ashr_i32 s7, s6, 31
	s_lshl_b64 s[6:7], s[6:7], 11
	s_or_b32 s6, s6, s26
	global_load_dword v190, v[66:67], off nt
	v_lshl_add_u64 v[66:67], v[154:155], 0, s[6:7]
	global_load_dword v192, v[66:67], off nt
	v_lshl_add_u64 v[66:67], v[156:157], 0, s[6:7]
	s_and_b64 s[6:7], s[4:5], exec
	s_cselect_b32 s2, 5, 0xe2
	s_or_b32 s6, s63, s2
	s_ashr_i32 s7, s6, 31
	s_lshl_b64 s[6:7], s[6:7], 11
	s_or_b32 s6, s6, s26
	global_load_dword v193, v[66:67], off nt
	v_lshl_add_u64 v[66:67], v[154:155], 0, s[6:7]
	global_load_dword v197, v[66:67], off nt
	v_lshl_add_u64 v[66:67], v[156:157], 0, s[6:7]
	s_and_b64 s[6:7], s[4:5], exec
	s_cselect_b32 s2, 6, 0xe1
	s_or_b32 s6, s63, s2
	s_ashr_i32 s7, s6, 31
	s_lshl_b64 s[6:7], s[6:7], 11
	s_or_b32 s6, s6, s26
	global_load_dword v198, v[66:67], off nt
	v_lshl_add_u64 v[66:67], v[154:155], 0, s[6:7]
	global_load_dword v200, v[66:67], off nt
	v_lshl_add_u64 v[66:67], v[156:157], 0, s[6:7]
	s_and_b64 s[6:7], s[4:5], exec
	s_cselect_b32 s2, 7, 0xe0
	s_or_b32 s6, s63, s2
	s_ashr_i32 s7, s6, 31
	s_lshl_b64 s[6:7], s[6:7], 11
	s_or_b32 s6, s6, s26
	global_load_dword v201, v[66:67], off nt
	v_lshl_add_u64 v[66:67], v[154:155], 0, s[6:7]
	s_add_i32 s2, s8, 0
	global_load_dword v214, v[66:67], off nt
	v_lshl_add_u64 v[66:67], v[156:157], 0, s[6:7]
	s_and_b64 s[6:7], s[4:5], exec
	s_cselect_b32 s6, 0, 0xe0
	s_or_b32 s6, s63, s6
	s_ashr_i32 s7, s6, 31
	s_lshl_b64 s[6:7], s[6:7], 11
	s_add_u32 s6, s20, s6
	s_addc_u32 s7, s21, s7
	s_add_u32 s6, s6, s26
	s_addc_u32 s7, s7, 0
	global_load_dword v216, v[66:67], off nt
	global_load_dwordx4 v[130:133], v146, s[6:7] offset:16 nt
	global_load_dwordx4 v[134:137], v146, s[6:7] nt
	v_add_u32_e32 v78, 18, v77
	v_cmp_gt_i32_e32 vcc, v78, v72
	v_mov_b32_e32 v75, s2
	s_lshl_b32 s8, s10, 5
	v_cndmask_b32_e64 v66, v167, 0, vcc
	v_cmp_lt_i32_e32 vcc, v78, v72
	v_mad_u32_u24 v78, v72, s25, v75
	v_and_b32_e32 v80, 12, v80
	v_cndmask_b32_e32 v67, 0, v168, vcc
	v_or_b32_e32 v191, v66, v67
	v_add_u32_e32 v66, 24, v77
	v_cmp_gt_i32_e32 vcc, v66, v72
	v_mad_u32_u24 v75, v72, s40, v75
	v_lshlrev_b32_e32 v196, 4, v73
	v_cndmask_b32_e64 v67, v167, 0, vcc
	v_cmp_lt_i32_e32 vcc, v66, v72
	v_lshlrev_b32_e32 v73, 3, v73
	s_and_b64 s[6:7], s[4:5], exec
	v_cndmask_b32_e32 v66, 0, v168, vcc
	v_or_b32_e32 v194, v67, v66
	v_add_u32_e32 v66, 26, v77
	v_cmp_gt_i32_e32 vcc, v66, v72
	s_cselect_b32 s16, 0x80, s41
	v_mul_lo_u32 v71, v71, s42
	v_cndmask_b32_e64 v67, v167, 0, vcc
	v_cmp_lt_i32_e32 vcc, v66, v72
	v_or_b32_e32 v72, s8, v72
	v_lshlrev_b32_e32 v72, 1, v72
	v_cndmask_b32_e32 v66, 0, v168, vcc
	v_or_b32_e32 v195, v67, v66
	v_bfe_u32 v66, v68, 2, 2
	v_and_b32_e32 v67, 16, v68
	v_or_b32_e32 v79, v77, v66
	v_cndmask_b32_e64 v77, v83, v77, s[4:5]
	v_or_b32_e32 v81, v80, v67
	v_lshlrev_b32_e32 v77, 8, v77
	v_or_b32_e32 v82, s8, v81
	v_add3_u32 v199, s37, v77, v72
	v_or_b32_e32 v66, v73, v66
	v_or3_b32 v67, s8, v67, v80
	v_cmp_lt_i32_e64 s[6:7], 0, v70
	v_cmp_lt_i32_e64 s[8:9], 1, v70
	v_cmp_lt_i32_e64 s[10:11], 2, v70
	v_cmp_gt_u32_e64 s[12:13], 16, v68
	v_lshlrev_b32_e32 v68, 3, v69
	v_mul_lo_u32 v69, v79, s42
	v_mul_lo_u32 v77, v70, s43
	v_mul_lo_u32 v79, v70, s44
	v_mul_lo_u32 v80, v70, s45
	v_lshl_or_b32 v70, v70, 3, 1
	s_add_u32 s14, s20, s26
	v_lshl_add_u32 v82, v82, 1, s2
	v_lshl_add_u32 v67, v67, 1, s2
	v_add_u32_e32 v71, s2, v71
	v_add_u32_e32 v72, s2, v74
	v_mul_lo_u32 v66, v66, s42
	v_lshl_add_u32 v74, v81, 1, s2
	v_mul_lo_u32 v81, v70, s25
	v_mul_lo_u32 v83, v70, s40
	v_mul_lo_u32 v70, v70, s42
	s_addc_u32 s15, s21, 0
	v_lshlrev_b32_e32 v2, 16, v6
	v_and_b32_e32 v3, 0xffff0000, v6
	v_lshlrev_b32_e32 v4, 16, v7
	v_and_b32_e32 v5, 0xffff0000, v7
	v_lshlrev_b32_e32 v6, 16, v8
	v_and_b32_e32 v7, 0xffff0000, v8
	v_lshlrev_b32_e32 v8, 16, v9
	v_and_b32_e32 v9, 0xffff0000, v9
	v_lshlrev_b32_e32 v10, 16, v14
	v_and_b32_e32 v11, 0xffff0000, v14
	v_lshlrev_b32_e32 v12, 16, v15
	v_and_b32_e32 v13, 0xffff0000, v15
	v_lshlrev_b32_e32 v14, 16, v16
	v_and_b32_e32 v15, 0xffff0000, v16
	v_lshlrev_b32_e32 v16, 16, v17
	v_and_b32_e32 v17, 0xffff0000, v17
	v_lshlrev_b32_e32 v18, 16, v22
	v_and_b32_e32 v19, 0xffff0000, v22
	v_lshlrev_b32_e32 v20, 16, v23
	v_and_b32_e32 v21, 0xffff0000, v23
	v_lshlrev_b32_e32 v22, 16, v24
	v_and_b32_e32 v23, 0xffff0000, v24
	v_lshlrev_b32_e32 v24, 16, v25
	v_and_b32_e32 v25, 0xffff0000, v25
	v_lshlrev_b32_e32 v26, 16, v30
	v_and_b32_e32 v27, 0xffff0000, v30
	v_lshlrev_b32_e32 v28, 16, v31
	v_and_b32_e32 v29, 0xffff0000, v31
	v_lshlrev_b32_e32 v30, 16, v32
	v_and_b32_e32 v31, 0xffff0000, v32
	v_lshlrev_b32_e32 v32, 16, v33
	v_and_b32_e32 v33, 0xffff0000, v33
	v_lshlrev_b32_e32 v34, 16, v38
	v_and_b32_e32 v35, 0xffff0000, v38
	v_lshlrev_b32_e32 v36, 16, v39
	v_and_b32_e32 v37, 0xffff0000, v39
	v_lshlrev_b32_e32 v38, 16, v40
	v_and_b32_e32 v39, 0xffff0000, v40
	v_lshlrev_b32_e32 v40, 16, v41
	v_and_b32_e32 v41, 0xffff0000, v41
	v_lshlrev_b32_e32 v42, 16, v46
	v_and_b32_e32 v43, 0xffff0000, v46
	v_lshlrev_b32_e32 v44, 16, v47
	v_and_b32_e32 v45, 0xffff0000, v47
	v_lshlrev_b32_e32 v46, 16, v48
	v_and_b32_e32 v47, 0xffff0000, v48
	v_lshlrev_b32_e32 v48, 16, v49
	v_and_b32_e32 v49, 0xffff0000, v49
	v_lshlrev_b32_e32 v50, 16, v54
	v_and_b32_e32 v51, 0xffff0000, v54
	v_lshlrev_b32_e32 v52, 16, v55
	v_and_b32_e32 v53, 0xffff0000, v55
	v_lshlrev_b32_e32 v54, 16, v56
	v_and_b32_e32 v55, 0xffff0000, v56
	v_lshlrev_b32_e32 v56, 16, v57
	v_and_b32_e32 v57, 0xffff0000, v57
	v_lshlrev_b32_e32 v58, 16, v62
	v_and_b32_e32 v59, 0xffff0000, v62
	v_lshlrev_b32_e32 v60, 16, v63
	v_and_b32_e32 v61, 0xffff0000, v63
	v_lshlrev_b32_e32 v62, 16, v64
	v_and_b32_e32 v63, 0xffff0000, v64
	v_lshlrev_b32_e32 v64, 16, v65
	v_and_b32_e32 v65, 0xffff0000, v65
	v_lshl_add_u64 v[158:159], s[14:15], 0, v[146:147]
	s_lshl_b32 s17, s16, 1
	s_mul_i32 s18, s16, 10
	v_add_u32_e32 v146, v78, v196
	v_add_u32_e32 v202, v82, v69
	v_add_u32_e32 v203, v75, v73
	v_add_u32_e32 v205, v74, v66
	v_add_u32_e32 v206, v67, v66
	v_add_u32_e32 v207, v71, v76
	v_add_u32_e32 v208, v72, v77
	v_add_u32_e32 v209, v72, v79
	v_add_u32_e32 v210, v72, v80
	v_add_u32_e32 v211, v72, v81
	v_add_u32_e32 v212, v72, v83
	v_add_u32_e32 v213, v72, v70
	v_add_u32_e32 v215, s2, v68
	s_branch .LBB0_1335

.LBB0_1344:
	s_or_b64 exec, exec, s[14:15]
	s_cmp_gt_u32 s98, 13
	s_cbranch_scc1 .LBB0_1334
	s_lshl_b32 s28, s28, 5
	s_add_i32 s29, s28, 32
	s_sub_i32 s30, 0xc7, s28
	s_and_b64 s[14:15], s[4:5], exec
	s_cselect_b32 s14, s29, s30
	s_add_i32 s14, s14, s63
	s_ashr_i32 s15, s14, 31
	s_lshl_b64 s[14:15], s[14:15], 11
	s_or_b64 s[14:15], s[14:15], s[26:27]
	v_lshl_add_u64 v[66:67], v[154:155], 0, s[14:15]
	s_sub_i32 s30, 0xc6, s28
	s_add_i32 s31, s28, 33
	global_load_dword v183, v[66:67], off nt
	v_lshl_add_u64 v[66:67], v[156:157], 0, s[14:15]
	s_and_b64 s[14:15], s[4:5], exec
	s_cselect_b32 s14, s31, s30
	s_add_i32 s14, s14, s63
	s_ashr_i32 s15, s14, 31
	s_lshl_b64 s[14:15], s[14:15], 11
	s_or_b64 s[14:15], s[14:15], s[26:27]
	global_load_dword v184, v[66:67], off nt
	v_lshl_add_u64 v[66:67], v[154:155], 0, s[14:15]
	s_sub_i32 s30, 0xc5, s28
	s_add_i32 s31, s28, 34
	global_load_dword v185, v[66:67], off nt
	v_lshl_add_u64 v[66:67], v[156:157], 0, s[14:15]
	s_and_b64 s[14:15], s[4:5], exec
	s_cselect_b32 s14, s31, s30
	s_add_i32 s14, s14, s63
	s_ashr_i32 s15, s14, 31
	s_lshl_b64 s[14:15], s[14:15], 11
	s_or_b64 s[14:15], s[14:15], s[26:27]
	global_load_dword v186, v[66:67], off nt
	v_lshl_add_u64 v[66:67], v[154:155], 0, s[14:15]
	s_sub_i32 s30, 0xc4, s28
	s_add_i32 s31, s28, 35
	global_load_dword v187, v[66:67], off nt
	v_lshl_add_u64 v[66:67], v[156:157], 0, s[14:15]
	s_and_b64 s[14:15], s[4:5], exec
	s_cselect_b32 s14, s31, s30
	s_add_i32 s14, s14, s63
	s_ashr_i32 s15, s14, 31
	s_lshl_b64 s[14:15], s[14:15], 11
	s_or_b64 s[14:15], s[14:15], s[26:27]
	global_load_dword v188, v[66:67], off nt
	v_lshl_add_u64 v[66:67], v[154:155], 0, s[14:15]
	s_sub_i32 s30, 0xc3, s28
	s_add_i32 s31, s28, 36
	global_load_dword v189, v[66:67], off nt
	v_lshl_add_u64 v[66:67], v[156:157], 0, s[14:15]
	s_and_b64 s[14:15], s[4:5], exec
	s_cselect_b32 s14, s31, s30
	s_add_i32 s14, s14, s63
	s_ashr_i32 s15, s14, 31
	s_lshl_b64 s[14:15], s[14:15], 11
	s_or_b64 s[14:15], s[14:15], s[26:27]
	global_load_dword v190, v[66:67], off nt
	v_lshl_add_u64 v[66:67], v[154:155], 0, s[14:15]
	s_sub_i32 s30, 0xc2, s28
	s_add_i32 s31, s28, 37
	global_load_dword v192, v[66:67], off nt
	v_lshl_add_u64 v[66:67], v[156:157], 0, s[14:15]
	s_and_b64 s[14:15], s[4:5], exec
	s_cselect_b32 s14, s31, s30
	s_add_i32 s14, s14, s63
	s_ashr_i32 s15, s14, 31
	s_lshl_b64 s[14:15], s[14:15], 11
	s_or_b64 s[14:15], s[14:15], s[26:27]
	global_load_dword v193, v[66:67], off nt
	v_lshl_add_u64 v[66:67], v[154:155], 0, s[14:15]
	s_sub_i32 s30, 0xc1, s28
	s_add_i32 s31, s28, 38
	global_load_dword v197, v[66:67], off nt
	v_lshl_add_u64 v[66:67], v[156:157], 0, s[14:15]
	s_and_b64 s[14:15], s[4:5], exec
	s_cselect_b32 s14, s31, s30
	s_add_i32 s14, s14, s63
	s_ashr_i32 s15, s14, 31
	s_lshl_b64 s[14:15], s[14:15], 11
	s_or_b64 s[14:15], s[14:15], s[26:27]
	global_load_dword v198, v[66:67], off nt
	v_lshl_add_u64 v[66:67], v[154:155], 0, s[14:15]
	s_sub_i32 s30, 0xc0, s28
	s_add_i32 s28, s28, 39
	global_load_dword v200, v[66:67], off nt
	v_lshl_add_u64 v[66:67], v[156:157], 0, s[14:15]
	s_and_b64 s[14:15], s[4:5], exec
	s_cselect_b32 s14, s28, s30
	s_add_i32 s14, s14, s63
	s_ashr_i32 s15, s14, 31
	s_lshl_b64 s[14:15], s[14:15], 11
	s_or_b64 s[14:15], s[14:15], s[26:27]
	global_load_dword v201, v[66:67], off nt
	v_lshl_add_u64 v[66:67], v[154:155], 0, s[14:15]
	global_load_dword v214, v[66:67], off nt
	v_lshl_add_u64 v[66:67], v[156:157], 0, s[14:15]
	s_and_b64 s[14:15], s[4:5], exec
	s_cselect_b32 s14, s29, s30
	s_add_i32 s14, s14, s63
	s_ashr_i32 s15, s14, 31
	s_lshl_b64 s[14:15], s[14:15], 11
	global_load_dword v216, v[66:67], off nt
	v_lshl_add_u64 v[66:67], v[158:159], 0, s[14:15]
	global_load_dwordx4 v[130:133], v[66:67], off offset:16 nt
	global_load_dwordx4 v[134:137], v[66:67], off nt
	s_branch .LBB0_1334
